# attention work queue: each ticket fetch also samples all 8 queue counters (mask broadcast with the ticket), exhausted queues skipped without an atomic round trip
# speedup vs baseline: 1.0004x; 1.0004x over previous
; #define LAS __attribute__((address_space(3)))
; __device__ __forceinline__ void attn_unit(const Args& a, LAS unsigned char* lds, float lam, int bh, int qb) {
;     ...
;     if (tid < 256) { const int rel = tid - 191; const int n = rel < 0 ? -rel : rel; int bucket;
;         if (n < 8) bucket = n; else { int lg = 31 - __clz(n * n); bucket = 2 + lg; if (bucket > 15) bucket = 15; }
;         if (rel > 0) bucket += 16;
;         tab[tid] = (a.in[23][bucket * 4 + h] - a.in[23][15 * 4 + h]) * LOG2E; }
;     const int kvr = tid >> 3, kc = (tid & 7) ^ ((kvr >> 1) & 7);
;     const bf16_t* ksrc = proj + (rowb + kvr) * NIN + 512 + h * 128 + 8 * kc;
;     const bf16_t* vsrc = VtG + ((size_t)bh * 128 + kvr) * VSTR + 8 * kc;
; __global__ void __launch_bounds__(512) fwd_kernel(Args a) {
;     ...
;         { float s1 = 0.f, s2 = 0.f;
;           for (int i = 0; i < 64; ++i) { s1 += a.in[10][i] * a.in[11][i]; s2 += a.in[12][i] * a.in[13][i]; }
;           lam = expf(s1) - expf(s2) + LAMBDA_INIT; }
;         unsigned* ctr = (unsigned*)ws;
;         LAS int* bc = (LAS int*)(lds + att::OFF_BC);
;         const int my = (int)(__builtin_amdgcn_s_getreg((3 << 11) | 20) & 7u);
;         for (int k = 0; k < 8; ++k) { const int bh = (my + k) & 7;
;             for (;;) { if (threadIdx.x == 0) *bc = (int)atomicAdd(ctr + 64 * bh, 1u);
.LBB0_483:
	v_add_u32_e32 v40, s0, v41
	ds_read_b128 v[6:9], v40
	ds_read_b128 v[10:13], v40 offset:16
	ds_read_b128 v[14:17], v40 offset:256
	ds_read_b128 v[18:21], v40 offset:272
	ds_read_b128 v[22:25], v40 offset:512
	ds_read_b128 v[26:29], v40 offset:528
	ds_read_b128 v[30:33], v40 offset:768
	ds_read_b128 v[34:37], v40 offset:784
	s_add_u32 s0, s0, 32
	s_addc_u32 s1, s1, 0
	s_cmpk_eq_i32 s0, 0x100
	s_waitcnt lgkmcnt(0)
	v_mov_b32_e32 v38, v6
	v_mov_b32_e32 v6, v8
	v_mov_b32_e32 v8, v10
	v_mov_b32_e32 v10, v12
	v_mov_b32_e32 v12, v14
	v_mov_b32_e32 v14, v16
	v_mov_b32_e32 v39, v22
	v_mov_b32_e32 v22, v7
	v_mov_b32_e32 v7, v24
	v_mov_b32_e32 v24, v9
	v_mov_b32_e32 v9, v26
	v_mov_b32_e32 v26, v11
	v_mov_b32_e32 v11, v28
	v_mov_b32_e32 v28, v13
	v_mov_b32_e32 v13, v30
	v_mov_b32_e32 v30, v15
	v_pk_fma_f32 v[2:3], v[38:39], v[12:13], v[2:3]
	v_mov_b32_e32 v15, v32
	v_pk_fma_f32 v[2:3], v[22:23], v[30:31], v[2:3]
	v_mov_b32_e32 v32, v17
	v_pk_fma_f32 v[2:3], v[6:7], v[14:15], v[2:3]
	v_mov_b32_e32 v16, v18
	v_mov_b32_e32 v17, v34
	v_pk_fma_f32 v[2:3], v[24:25], v[32:33], v[2:3]
	v_mov_b32_e32 v34, v19
	v_pk_fma_f32 v[2:3], v[8:9], v[16:17], v[2:3]
	v_mov_b32_e32 v18, v20
	v_mov_b32_e32 v19, v36
	v_pk_fma_f32 v[2:3], v[26:27], v[34:35], v[2:3]
	v_mov_b32_e32 v36, v21
	v_pk_fma_f32 v[2:3], v[10:11], v[18:19], v[2:3]
	s_nop 0
	v_pk_fma_f32 v[2:3], v[28:29], v[36:37], v[2:3]
	s_cbranch_scc0 .LBB0_483
	v_mul_f32_e32 v4, 0x3fb8aa3b, v2
	s_mov_b32 s0, 0x3fb8aa3b
	v_rndne_f32_e32 v5, v4
	v_sub_f32_e32 v6, v4, v5
	v_fma_f32 v4, v2, s0, -v4
	v_fmac_f32_e32 v4, 0x32a5705f, v2
	v_add_f32_e32 v4, v6, v4
	v_exp_f32_e32 v4, v4
	v_cvt_i32_f32_e32 v5, v5
	s_mov_b32 s1, 0xc2ce8ed0
	v_cmp_ngt_f32_e32 vcc, s1, v2
	s_mov_b32 s2, 0x42b17218
	v_ldexp_f32 v4, v4, v5
	v_mul_f32_e32 v5, 0x3fb8aa3b, v3
	v_rndne_f32_e32 v6, v5
	v_sub_f32_e32 v7, v5, v6
	v_fma_f32 v5, v3, s0, -v5
	v_fmac_f32_e32 v5, 0x32a5705f, v3
	v_add_f32_e32 v5, v7, v5
	v_exp_f32_e32 v5, v5
	v_cvt_i32_f32_e32 v6, v6
	v_cndmask_b32_e32 v4, 0, v4, vcc
	v_mov_b32_e32 v7, 0x7f800000
	v_cmp_nlt_f32_e32 vcc, s2, v2
	v_lshrrev_b32_e32 v8, 4, v1
	v_mov_b32_e32 v161, 0
	v_cndmask_b32_e32 v2, v7, v4, vcc
	v_ldexp_f32 v4, v5, v6
	v_cmp_ngt_f32_e32 vcc, s1, v3
	v_bfe_u32 v5, v1, 5, 1
	s_add_u32 s16, s86, 0x7000000
	v_cndmask_b32_e32 v4, 0, v4, vcc
	v_cmp_nlt_f32_e32 vcc, s2, v3
	s_movk_i32 s2, 0x100
	v_cmp_gt_u32_e64 s[4:5], s2, v1
	v_cndmask_b32_e32 v3, v7, v4, vcc
	v_sub_f32_e32 v2, v2, v3
	s_movk_i32 s2, 0xbf
	v_add_f32_e32 v159, 0x3e4ccccd, v2
	v_sub_co_u32_e32 v2, vcc, s2, v1
	v_subrev_co_u32_e64 v4, s[6:7], s2, v1
	v_and_b32_e32 v3, 63, v1
	s_nop 0
	v_cndmask_b32_e64 v2, v4, v2, s[6:7]
	v_mul_i32_i24_e32 v4, v2, v2
	v_ffbh_u32_e32 v4, v4
	v_sub_u32_e32 v4, 33, v4
	v_min_u32_e32 v4, 15, v4
	v_cmp_gt_u32_e64 s[6:7], 8, v2
	s_mov_b64 s[2:3], 0x1d000000
	v_lshl_add_u32 v220, v3, 2, 0
	v_cndmask_b32_e64 v2, v4, v2, s[6:7]
	v_lshlrev_b32_e32 v2, 2, v2
	v_or_b32_e32 v4, 64, v2
	v_cndmask_b32_e32 v209, v2, v4, vcc
	v_xor_b32_e32 v2, v8, v1
	v_lshlrev_b32_e32 v2, 3, v2
	v_and_b32_e32 v2, 56, v2
	v_lshlrev_b32_e32 v160, 1, v2
	v_lshl_add_u64 v[6:7], s[86:87], 0, v[160:161]
	v_lshl_add_u64 v[162:163], v[6:7], 0, s[2:3]
	v_lshlrev_b32_e32 v6, 3, v1
	v_cmp_gt_u32_e64 s[6:7], 32, v3
	v_bitop3_b32 v3, v8, 7, v1 bitop3:0x48
	v_and_b32_e32 v158, 31, v1
	s_addc_u32 s17, s87, 0
	s_add_i32 s41, 0, 0x20000
	v_and_b32_e32 v212, 0x70, v6
	v_lshlrev_b32_e32 v6, 2, v5
	v_lshlrev_b32_e32 v160, 4, v3
	s_getreg_b32 s40, hwreg(HW_REG_XCC_ID, 0, 4)
	v_lshlrev_b32_e32 v4, 3, v5
	v_lshlrev_b32_e32 v213, 4, v5
	v_lshlrev_b32_e32 v214, 7, v158
	v_add_u32_e32 v215, 0xbf, v6
	s_add_u32 s43, s86, 0x3000000
	v_sub_u32_e32 v221, v6, v158
	v_lshl_add_u64 v[6:7], s[86:87], 0, v[160:161]
	s_mov_b64 s[2:3], 0x71c0480
	v_lshlrev_b32_e32 v168, 1, v2
	s_movk_i32 s28, 0xff80
	v_mbcnt_lo_u32_b32 v2, -1, 0
	s_mov_b32 s15, 0
	v_cmp_eq_u32_e64 s[0:1], 0, v1
	v_lshl_add_u32 v210, v1, 2, s41
	v_lshrrev_b32_e32 v211, 3, v1
	v_add_u32_e32 v216, 0, v214
	v_or_b32_e32 v217, 32, v213
	v_or_b32_e32 v218, 64, v213
	s_movk_i32 s42, 0x60
	v_or_b32_e32 v219, 0x60, v213
	s_addc_u32 s44, s87, 0
	v_lshlrev_b32_e32 v164, 13, v5
	v_mov_b32_e32 v165, v161
	v_lshl_add_u64 v[166:167], v[6:7], 0, s[2:3]
	s_mov_b64 s[18:19], 0x202000
	s_mov_b64 s[20:21], 0x202180
	s_mov_b64 s[22:23], 0x180
	s_mov_b64 s[24:25], 0x150480
	s_mov_b64 s[26:27], 0x150400
	s_add_i32 s45, 0, 0x20c00
	s_movk_i32 s46, 0x7f
	v_lshlrev_b32_e32 v160, 1, v4
	s_mov_b32 s47, 0x8000
	s_mov_b32 s52, 0xc000
	s_mov_b32 s53, 0x41400000
	s_mov_b32 s29, -1
	s_mov_b64 s[30:31], 0x70000
	v_mov_b32_e32 v222, 0x3727c5ac
	s_mov_b32 s54, 0xf800000
	v_mov_b32_e32 v223, 0x260
	s_mov_b32 s55, 0x3f4ccccd
	s_movk_i32 s56, 0x1000
	s_movk_i32 s57, 0x5000
	s_mov_b32 s58, 0x9000
	s_mov_b32 s59, 0xd000
	v_mbcnt_hi_u32_b32 v224, -1, v2
	s_mov_b32 s60, s40
	s_mov_b32 s61, 0
	s_mov_b32 s100, 0
	s_branch .LBB0_486
.LBB0_485:
	s_add_i32 s61, s61, 1
	s_add_i32 s60, s60, 1
	s_cmp_eq_u32 s61, 8
	s_cbranch_scc1 .LBB0_549
	s_add_i32 s2, s61, s40
	s_and_b32 s2, s2, 7
	s_lshr_b32 s2, s100, s2
	s_bitcmp1_b32 s2, 0
	s_cbranch_scc1 .LBB0_485

; #define SYNC() __syncthreads()
; __global__ void __launch_bounds__(512) fwd_kernel(Args a) {
;     ...
;             for (;;) { if (threadIdx.x == 0) *bc = (int)atomicAdd(ctr + 64 * bh, 1u);
;                 SYNC(); const int idx = *bc; SYNC();
;                 if (idx >= 128) break;
;                 att::attn_unit(a, lds, lam, bh, 127 - idx); } }
.LBB0_489:
	s_and_saveexec_b64 s[2:3], s[0:1]
	s_cbranch_execz .LBB0_493
	s_mov_b64 s[10:11], exec
	v_mbcnt_lo_u32_b32 v2, s10, 0
	v_mbcnt_hi_u32_b32 v2, s11, v2
	v_cmp_eq_u32_e32 vcc, 0, v2
	s_and_saveexec_b64 s[8:9], vcc
	s_cbranch_execz .LBB0_492
	s_bcnt1_i32_b64 s10, s[10:11]
	v_mov_b32_e32 v3, s10
	global_atomic_add v3, v161, v3, s[34:35] sc0
	global_load_dword v240, v161, s[86:87] sc1
	global_load_dword v241, v161, s[86:87] offset:256 sc1
	global_load_dword v242, v161, s[86:87] offset:512 sc1
	global_load_dword v243, v161, s[86:87] offset:768 sc1
	global_load_dword v244, v161, s[86:87] offset:1024 sc1
	global_load_dword v245, v161, s[86:87] offset:1280 sc1
	global_load_dword v246, v161, s[86:87] offset:1536 sc1
	global_load_dword v247, v161, s[86:87] offset:1792 sc1
.LBB0_492:
	s_or_b64 exec, exec, s[8:9]
	s_waitcnt vmcnt(0)
	v_readfirstlane_b32 s8, v3
	v_mov_b32_e32 v248, 0
	v_cmp_lt_i32_e32 vcc, s46, v240
	s_nop 1
	v_cndmask_b32_e64 v249, 0, 1, vcc
	v_lshl_or_b32 v248, v249, 24, v248
	v_cmp_lt_i32_e32 vcc, s46, v241
	s_nop 1
	v_cndmask_b32_e64 v249, 0, 1, vcc
	v_lshl_or_b32 v248, v249, 25, v248
	v_cmp_lt_i32_e32 vcc, s46, v242
	s_nop 1
	v_cndmask_b32_e64 v249, 0, 1, vcc
	v_lshl_or_b32 v248, v249, 26, v248
	v_cmp_lt_i32_e32 vcc, s46, v243
	s_nop 1
	v_cndmask_b32_e64 v249, 0, 1, vcc
	v_lshl_or_b32 v248, v249, 27, v248
	v_cmp_lt_i32_e32 vcc, s46, v244
	s_nop 1
	v_cndmask_b32_e64 v249, 0, 1, vcc
	v_lshl_or_b32 v248, v249, 28, v248
	v_cmp_lt_i32_e32 vcc, s46, v245
	s_nop 1
	v_cndmask_b32_e64 v249, 0, 1, vcc
	v_lshl_or_b32 v248, v249, 29, v248
	v_cmp_lt_i32_e32 vcc, s46, v246
	s_nop 1
	v_cndmask_b32_e64 v249, 0, 1, vcc
	v_lshl_or_b32 v248, v249, 30, v248
	v_cmp_lt_i32_e32 vcc, s46, v247
	s_nop 1
	v_cndmask_b32_e64 v249, 0, 1, vcc
	v_lshl_or_b32 v248, v249, 31, v248
	v_readfirstlane_b32 s9, v248
	v_mov_b32_e32 v3, s45
	s_nop 0
	v_add_u32_e32 v2, s8, v2
	v_or_b32_e32 v2, s9, v2
	ds_write_b32 v3, v2
.LBB0_493:
	s_or_b64 exec, exec, s[2:3]
	v_mov_b32_e32 v2, s45
	s_waitcnt lgkmcnt(0)
	s_barrier
	ds_read_b32 v2, v2
	s_mov_b64 s[2:3], -1
	s_waitcnt lgkmcnt(0)
	s_barrier
	v_lshrrev_b32_e32 v3, 24, v2
	v_and_b32_e32 v2, 0xffffff, v2
	v_readfirstlane_b32 s101, v3
	s_or_b32 s100, s100, s101
	v_cmp_lt_i32_e32 vcc, s46, v2
	v_readfirstlane_b32 s73, v2
	s_cbranch_vccnz .LBB0_488
	s_waitcnt vmcnt(0)
	v_readfirstlane_b32 s10, v1
	s_and_saveexec_b64 s[2:3], s[4:5]
	s_cbranch_execz .LBB0_496
	global_load_dword v2, v[170:171], off
	global_load_dword v3, v161, s[36:37]
	s_waitcnt vmcnt(0)
	v_sub_f32_e32 v2, v2, v3
	v_mul_f32_e32 v2, 0x3fb8aa3b, v2
	ds_write_b32 v210, v2

; #define LAS __attribute__((address_space(3)))
; __global__ void __launch_bounds__(512) fwd_kernel(Args a) {
;     extern __shared__ __attribute__((aligned(16))) unsigned char lds_raw[];
;     LAS unsigned char* lds = (LAS unsigned char*)lds_raw;
;     unsigned char* ws = a.ws;
;     const int G = gridDim.x, bx = blockIdx.x;
amdhsa.kernels:
  - .agpr_count:     0
    .args:
      - .offset:         0
        .size:           216
        .value_kind:     by_value
      - .offset:         216
        .size:           4
        .value_kind:     hidden_block_count_x
      - .offset:         220
        .size:           4
        .value_kind:     hidden_block_count_y
      - .offset:         224
        .size:           4
        .value_kind:     hidden_block_count_z
      - .offset:         228
        .size:           2
        .value_kind:     hidden_group_size_x
      - .offset:         230
        .size:           2
        .value_kind:     hidden_group_size_y
      - .offset:         232
        .size:           2
        .value_kind:     hidden_group_size_z
      - .offset:         234
        .size:           2
        .value_kind:     hidden_remainder_x
      - .offset:         236
        .size:           2
        .value_kind:     hidden_remainder_y
      - .offset:         238
        .size:           2
        .value_kind:     hidden_remainder_z
      - .offset:         256
        .size:           8
        .value_kind:     hidden_global_offset_x
      - .offset:         264
        .size:           8
        .value_kind:     hidden_global_offset_y
      - .offset:         272
        .size:           8
        .value_kind:     hidden_global_offset_z
      - .offset:         280
        .size:           2
        .value_kind:     hidden_grid_dims
      - .offset:         304
        .size:           8
        .value_kind:     hidden_multigrid_sync_arg
      - .offset:         336
        .size:           4
        .value_kind:     hidden_dynamic_lds_size
    .group_segment_fixed_size: 0
    .kernarg_segment_align: 8
    .kernarg_segment_size: 472
    .language:       OpenCL C
    .language_version:
      - 2
      - 0
    .max_flat_workgroup_size: 512
    .name:           _Z10fwd_kernel4Args
    .private_segment_fixed_size: 0
    .sgpr_count:     108
    .sgpr_spill_count: 69
    .symbol:         _Z10fwd_kernel4Args.kd
    .uniform_work_group_size: 1
    .uses_dynamic_stack: false
    .vgpr_count:     256
    .vgpr_spill_count: 0
    .wavefront_size: 64
